# scan workgroups poll the prep-done counter without the 128-cycle sleep between polls
# baseline (speedup 1.0000x reference)
; __device__ __forceinline__ int lane_id() { int l; asm volatile("v_mbcnt_lo_u32_b32 %0, -1, 0\n\tv_mbcnt_hi_u32_b32 %0, -1, %0" : "=v"(l)); return l; }
; __global__ void __launch_bounds__(NTHREADS, 2) mega_fwd(Params p_in) {
;     ...
;         if (wave_id == 0 && lane_id() == 0) { unsigned* pc = (unsigned*)(ws + WS_PREPCTR); while (__hip_atomic_load(pc, __ATOMIC_RELAXED, __HIP_MEMORY_SCOPE_AGENT) < (unsigned)nb) __builtin_amdgcn_s_sleep(2); }
.LBB0_395:
	s_sleep 0
	global_load_dword v1, v0, s[6:7] sc1
	s_waitcnt vmcnt(0)
	v_cmp_gt_u32_e32 vcc, s33, v1
	s_cbranch_vccnz .LBB0_395
